# 7 XCD-local seams (S4,S5,S8,S9,S11,S12,S14) with bid%8-group barrier + runtime placement check; attention and LRU work remapped so batch b runs on group b
# speedup vs baseline: 1.0237x; 1.0237x over previous
; #define LAS __attribute__((address_space(3)))
; __device__ __forceinline__ unsigned xb_add(unsigned* p, unsigned v) { return __hip_atomic_fetch_add(p, v, __ATOMIC_RELAXED, __HIP_MEMORY_SCOPE_AGENT); }
; __device__ __forceinline__ unsigned xb_xcc_id() { return (unsigned)__builtin_amdgcn_s_getreg((3 << 11) | 20) & 0xFu; }
; __device__ __forceinline__ XcdBarrier xcd_barrier_post(unsigned* bar, volatile LAS unsigned* st, bool is_t0) {
;     XcdBarrier b; b.bar = bar; b.x = xb_xcc_id(); b.st = st;
;     if (is_t0) (void)xb_add(&bar[XB_XCNT(b.x)], 1u);
;     return b;
; }
; __global__ void __launch_bounds__(512, 2) fwd_megakernel(Args a) {
;     ...
;     volatile LAS unsigned* MISC = (volatile LAS unsigned*)(lds + 131072 + 4096);
;     if (tid < 2) MISC[tid] = 0u;
;     __syncthreads();
;     const XcdBarrier xbar = xcd_barrier_post((unsigned*)(ws + WS_CTL), MISC, tid == 0);
_Z14fwd_megakernel4Args:
	s_load_dwordx4 s[44:47], s[0:1], 0xe8
	s_add_u32 s4, s0, 0xf0
	v_and_b32_e32 v1, 0x3ff, v0
	s_mov_b32 s33, s2
	s_addc_u32 s5, s1, 0
	v_readfirstlane_b32 s83, v1
	v_cmp_gt_u32_e32 vcc, 2, v1
	s_and_saveexec_b64 s[2:3], vcc
	v_lshl_add_u32 v2, v1, 2, 0
	v_add_u32_e32 v2, 0x21000, v2
	v_mov_b32_e32 v3, 0
	ds_write_b32 v2, v3
	s_or_b64 exec, exec, s[2:3]
	s_waitcnt lgkmcnt(0)
	s_barrier
	s_getreg_b32 s2, hwreg(HW_REG_XCC_ID, 0, 4)
	v_cmp_eq_u32_e32 vcc, 0, v1
	s_and_b32 s81, s2, 15
	s_and_saveexec_b64 s[2:3], vcc
	s_cbranch_execz .LBB0_5
	s_mov_b64 s[6:7], exec
	v_mbcnt_lo_u32_b32 v2, s6, 0
	v_mbcnt_hi_u32_b32 v2, s7, v2
	v_cmp_eq_u32_e32 vcc, 0, v2
	s_and_b64 s[8:9], exec, vcc
	s_mov_b64 exec, s[8:9]
	s_cbranch_execz .LBB0_5
	s_lshl_b32 s8, s81, 8
	s_bcnt1_i32_b64 s6, s[6:7]
	v_mov_b32_e32 v2, s8
	v_mov_b32_e32 v3, s6
	global_atomic_add v2, v3, s[44:45] offset:1024
	s_lshl_b32 s98, 1, s81
	s_and_b32 s99, s33, 7
	s_lshl_b32 s99, s99, 2
	s_addk_i32 s99, 0x5000
	v_mov_b32_e32 v2, s99
	v_mov_b32_e32 v3, s98
	global_atomic_or v2, v3, s[44:45]

; #define PG8_WAIT_V(n) asm volatile("s_waitcnt vmcnt(" #n ")" ::: "memory")
; template <class Epi, class Sched, bool ALIGN_EPI = false, bool SP2 = false>
; __device__ __forceinline__ void gemm_phase(PG8_LAS unsigned char* lds, const Gemm g, const Sched& S, const Epi& E, int wave_s) {
;     int tid = wave_s * 64 + lane_id_(); asm volatile("" : "+v"(tid));
;     const int wid = __builtin_amdgcn_readfirstlane(tid >> 6), lane = tid & 63, wr = wid >> 2, wc = wid & 3, fr = lane & 15, fq = lane >> 4;
;     const int K = g.K, nt = K / BK;
;     unsigned voffA[2], voffB[2];
; #pragma unroll
;     for (int i = 0; i < 2; ++i) { int R, C; stage_rc(tid * 16 + i * 8192, R, C); const int Rb = Epi::PERM ? ((R & ~31) + perm32(R & 31)) : R;
;         voffA[i] = (unsigned)(R * K + C) * 2u; voffB[i] = (unsigned)(Rb * K + C) * 2u; }
;     const size_t kstep = (size_t)(BK * 2);
;     const size_t hstep = (size_t)HALF * K * 2;
;     const size_t tstep = 2 * hstep;
;     const unsigned ldsw = (unsigned)wid * 1024u;
;     const int aoff = lds_byte(wr * 64 + fr, fq * 8), boff = lds_byte(wc * 32 + fr, fq * 8);
;     ...
;     Unit cur, nxt; int ui = 0; bool peeled = false;
;     if (!S.next(0, cur)) return;
;     if constexpr (Epi::NPRE > 0) E.prefetch(lds, wid, cur, wr, fr, fq);
;     f32x4 acc[2][2][4][2];
; #pragma unroll
;     for (int a = 0; a < 2; ++a)
; #pragma unroll
;         for (int b = 0; b < 2; ++b)
; #pragma unroll
;             for (int m = 0; m < 4; ++m)
; #pragma unroll
;                 for (int n = 0; n < 2; ++n) acc[a][b][m][n] = (f32x4){0.f, 0.f, 0.f, 0.f};
;     bf16x8 At[4][2], B0[2][2], B1[2][2];
;     const char* cA = (const char*)g.A + (size_t)cur.pm * tstep; const char* cB = (const char*)g.Bt + (size_t)cur.pn * tstep;
;     S.a_ready(cur);
;     if constexpr (SP2) {
;         PG8_STAGE(PG8_SB(0, 0), cB, voffB); PG8_STAGE(PG8_SB(0, 1), cB + hstep, voffB); PG8_STAGE(PG8_SA(0, 0), cA, voffA); PG8_STAGE(PG8_SA(0, 1), cA + hstep, voffA);
;         if (wr == 1) PG8_BAR;
;         PG8_WAIT_V(2); PG8_BAR;
;         PG8_STAGE(PG8_SB(1, 0), cB + kstep, voffB); PG8_STAGE(PG8_SA(1, 0), cA + kstep, voffA); PG8_STAGE(PG8_SB(1, 1), cB + hstep + kstep, voffB);
;         PG8_WAIT_V(6); PG8_BAR;
;     } else {
;         PG8_STAGE(PG8_SB(0, 0), cB, voffB); PG8_STAGE(PG8_SA(0, 0), cA, voffA); PG8_STAGE(PG8_SB(0, 1), cB + hstep, voffB); PG8_STAGE(PG8_SA(0, 1), cA + hstep, voffA);
.LBB0_98:
	s_add_u32 s48, s44, 0x5400000
	s_addc_u32 s49, s45, 0
	s_add_u32 s50, s44, 0x7400000
	s_addc_u32 s51, s45, 0
	s_add_u32 s56, s44, 0x300000
	s_addc_u32 s57, s45, 0
	s_andn2_b32 s83, s83, 63
	s_waitcnt lgkmcnt(0)
	s_barrier
	v_mbcnt_lo_u32_b32 v0, -1, 0
	v_mbcnt_hi_u32_b32 v0, -1, v0
	v_and_b32_e32 v0, 7, v0
	v_lshlrev_b32_e32 v0, 2, v0
	v_add_u32_e32 v0, 0x5000, v0
	global_load_dword v1, v0, s[44:45] sc1
	s_waitcnt vmcnt(0)
	v_add_u32_e32 v2, -1, v1
	v_and_b32_e32 v2, v2, v1
	v_cmp_eq_u32_e64 s[98:99], 0, v2
	v_cmp_ne_u32_e64 s[100:101], 0, v1
	s_nop 3
	s_and_b64 s[98:99], s[98:99], s[100:101]
	s_cmp_eq_u64 s[98:99], -1
	s_cselect_b32 s101, 1, 0
	s_cmpk_eq_u32 s46, 0x100
	s_cselect_b32 s101, s101, 0
	v_mbcnt_lo_u32_b32 v0, -1, 0
	v_mbcnt_hi_u32_b32 v0, -1, v0
	s_cmpk_lt_i32 s33, 0x580
	v_add_u32_e32 v2, s83, v0
	s_cselect_b64 s[70:71], -1, 0
	s_cmpk_gt_i32 s33, 0x57f
	v_readfirstlane_b32 s10, v2
	s_cbranch_scc1 .LBB0_114
	v_lshlrev_b32_e32 v0, 4, v2
	v_add_u32_e32 v1, 0x2000, v0
	v_ashrrev_i32_e32 v3, 31, v1
	v_lshrrev_b32_e32 v3, 22, v3
	v_add_u32_e32 v3, v1, v3
	v_ashrrev_i32_e32 v3, 10, v3
	v_mul_i32_i24_e32 v4, 0x400, v3
	v_sub_u32_e32 v1, v1, v4
	v_lshrrev_b32_e32 v4, 4, v1
	v_bitop3_b32 v1, v4, v1, 32 bitop3:0x6c
	v_ashrrev_i32_e32 v4, 31, v1
	v_lshrrev_b32_e32 v4, 26, v4
	v_add_u32_e32 v4, v1, v4
	v_lshlrev_b32_e32 v6, 3, v3
	v_ashrrev_i32_e32 v5, 6, v4
	v_and_b32_e32 v6, -16, v6
	v_and_b32_e32 v4, 0xc0, v4
	v_add_u32_e32 v6, v5, v6
	v_sub_u32_e32 v1, v1, v4
	v_mov_b32_e32 v4, 1
	v_and_b32_e32 v5, 3, v5
	s_mov_b32 s3, 0x1fffe0
	v_lshrrev_b32_e32 v7, 2, v6
	v_lshlrev_b32_e32 v8, 1, v6
	v_lshlrev_b32_e32 v3, 5, v3
	v_ashrrev_i16_sdwa v1, v4, sext(v1) dst_sel:DWORD dst_unused:UNUSED_PAD src0_sel:DWORD src1_sel:BYTE_0
	v_and_or_b32 v5, v6, s3, v5
	v_and_b32_e32 v7, 4, v7
	v_and_b32_e32 v8, 24, v8
	v_and_b32_e32 v3, 32, v3
	v_bfe_i32 v1, v1, 0, 16
	v_or3_b32 v5, v5, v7, v8
	v_add_lshl_u32 v1, v3, v1, 1
	v_lshl_add_u32 v132, v5, 11, v1
	v_lshl_add_u32 v134, v6, 11, v1
	v_bfe_i32 v1, v2, 27, 1
	v_lshrrev_b32_e32 v1, 22, v1
	v_add_u32_e32 v1, v0, v1
	v_and_b32_e32 v1, 0xfffffc00, v1
	v_sub_u32_e32 v0, v0, v1
	v_lshrrev_b32_e32 v1, 4, v0
	v_ashrrev_i32_e32 v5, 31, v2
	v_bitop3_b32 v0, v1, v0, 32 bitop3:0x6c
	v_lshrrev_b32_e32 v5, 26, v5
	v_ashrrev_i32_e32 v1, 31, v0
	v_add_u32_e32 v5, v2, v5
	s_ashr_i32 s16, s10, 8
	s_ashr_i32 s11, s10, 6
	v_lshrrev_b32_e32 v1, 26, v1
	v_ashrrev_i32_e32 v5, 6, v5
	s_lshl_b32 s38, s11, 10
	s_lshl_b32 s2, s16, 6
	v_add_u32_e32 v1, v0, v1
	v_lshlrev_b32_e32 v6, 3, v5
	s_add_u32 s14, s44, 0x10000
	v_ashrrev_i32_e32 v3, 6, v1
	v_and_b32_e32 v6, -16, v6
	s_addc_u32 s15, s45, 0
	v_add_u32_e32 v6, v3, v6
	v_and_b32_e32 v3, 3, v3
	s_ashr_i32 s39, s33, 31
	v_and_or_b32 v3, v6, s3, v3
	s_lshr_b32 s3, s39, 29
	s_add_i32 s3, s33, s3
	s_ashr_i32 s6, s3, 3
	s_and_b32 s3, s3, -8
	s_sub_i32 s3, s33, s3
	s_cmp_lt_i32 s3, 0
	s_movk_i32 s40, 0xb1
	s_cselect_b32 s7, s40, 0xb0
	s_mul_i32 s3, s3, s7
	s_add_i32 s3, s3, s6
	s_mul_hi_i32 s6, s3, 0x2e8ba2e9
	s_lshr_b32 s7, s6, 31
	s_ashr_i32 s6, s6, 5
	s_add_i32 s6, s6, s7
	s_lshl_b32 s7, s6, 3
	s_mulk_i32 s6, 0xb0
	s_sub_i32 s3, s3, s6
	s_sext_i32_i16 s6, s3
	s_bfe_u32 s6, s6, 0x3001c
	s_add_i32 s8, s3, s6
	s_sext_i32_i16 s6, s8
	s_and_b32 s8, s8, 0xfff8
	s_sub_i32 s3, s3, s8
	s_sext_i32_i16 s3, s3
	s_add_i32 s20, s7, s3
	v_and_b32_e32 v1, 0xc0, v1
	s_lshl_b32 s7, s11, 9
	s_lshl_b32 s8, s20, 8
	v_sub_u32_e32 v0, v0, v1
	s_add_i32 s7, s7, 0
	s_ashr_i32 s9, s8, 31
	v_lshrrev_b32_e32 v7, 2, v6
	v_lshlrev_b32_e32 v8, 1, v6
	v_lshlrev_b32_e32 v5, 5, v5
	v_ashrrev_i16_sdwa v0, v4, sext(v0) dst_sel:DWORD dst_unused:UNUSED_PAD src0_sel:DWORD src1_sel:BYTE_0
	s_lshr_b32 s6, s6, 3
	s_ashr_i32 s3, s2, 31
	s_add_i32 s41, s7, 0x21400
	s_lshl_b64 s[8:9], s[8:9], 2
	v_and_b32_e32 v7, 4, v7
	v_and_b32_e32 v8, 24, v8
	v_and_b32_e32 v5, 32, v5
	v_bfe_i32 v0, v0, 0, 16
	s_add_u32 s8, s14, s8
	v_or3_b32 v3, v3, v7, v8
	v_add_lshl_u32 v0, v5, v0, 1
	s_addc_u32 s9, s15, s9
	s_lshl_b64 s[12:13], s[2:3], 2
	v_lshl_add_u32 v136, v3, 11, v0
	v_lshl_add_u32 v138, v6, 11, v0
	v_mbcnt_lo_u32_b32 v3, -1, 0
	v_mbcnt_hi_u32_b32 v3, -1, v3
	s_add_u32 s8, s8, s12
	v_and_b32_e32 v0, 15, v3
	v_lshlrev_b32_e32 v1, 2, v3
	v_and_b32_e32 v4, 0xffffff80, v1
	s_addc_u32 s9, s9, s13
	v_lshlrev_b32_e32 v0, 2, v0
	v_mov_b32_e32 v1, 0
	v_ashrrev_i32_e32 v5, 31, v4
	v_lshl_add_u64 v[6:7], s[8:9], 0, v[0:1]
	v_lshlrev_b32_e32 v0, 3, v3
	v_lshl_add_u64 v[4:5], v[4:5], 2, v[6:7]
	v_and_b32_e32 v0, 0x80, v0
	v_lshl_add_u64 v[4:5], v[4:5], 0, v[0:1]
	s_mov_b32 m0, s41
	s_ashr_i32 s21, s20, 31
	s_bfe_i64 s[18:19], s[6:7], 0x100000
	global_load_lds_dword v[4:5], off
	s_add_i32 m0, s7, 0x21500
	s_lshl_b64 s[8:9], s[20:21], 19
	s_lshl_b64 s[18:19], s[18:19], 19
	s_add_u32 s22, s56, s18
	v_lshl_add_u64 v[4:5], v[4:5], 0, 64
	s_addc_u32 s23, s57, s19
	s_add_i32 s42, s38, 0
	global_load_lds_dword v[4:5], off
	s_mov_b64 s[18:19], s[22:23]
	s_add_i32 m0, s42, 0x10000
	s_mov_b32 s7, 0
	global_load_lds_dwordx4 v136, s[18:19]
	s_add_i32 m0, s42, 0x12000
	v_mov_b32_e32 v137, v1
	global_load_lds_dwordx4 v132, s[18:19]
	s_add_u32 s18, s22, 0x40000
	s_addc_u32 s19, s23, 0
	s_add_i32 m0, s42, 0x14000
	v_mov_b32_e32 v133, v1
	global_load_lds_dwordx4 v136, s[18:19]
	s_add_i32 m0, s42, 0x16000
	s_add_u32 s24, s48, s8
	s_addc_u32 s25, s49, s9
	global_load_lds_dwordx4 v132, s[18:19]
	s_mov_b64 s[8:9], s[24:25]
	s_mov_b32 m0, s42
	s_add_i32 s43, s42, 0x2000
	v_mov_b32_e32 v139, v1
	global_load_lds_dwordx4 v138, s[8:9]
	s_mov_b32 m0, s43
	v_mov_b32_e32 v135, v1
	global_load_lds_dwordx4 v134, s[8:9]
	s_add_u32 s8, s24, 0x40000
	s_addc_u32 s9, s25, 0
	s_add_i32 s52, s42, 0x4000
	s_mov_b32 m0, s52
	s_add_i32 s53, s42, 0x6000
	s_cmp_eq_u32 s16, 1
	global_load_lds_dwordx4 v138, s[8:9]
	s_mov_b32 m0, s53
	s_nop 0
	global_load_lds_dwordx4 v134, s[8:9]
	s_cselect_b64 s[8:9], -1, 0
	s_cmp_lg_u32 s16, 1
	s_cbranch_scc1 .LBB0_101
	s_barrier

; __device__ __forceinline__ int lane_id_() { int l; asm volatile("v_mbcnt_lo_u32_b32 %0, -1, 0\n\tv_mbcnt_hi_u32_b32 %0, -1, %0" : "=v"(l)); return l; }
; __device__ __forceinline__ unsigned xb_ld(unsigned* p)              { return __hip_atomic_load(p, __ATOMIC_RELAXED, __HIP_MEMORY_SCOPE_AGENT); }
; __device__ __forceinline__ unsigned xb_add(unsigned* p, unsigned v) { return __hip_atomic_fetch_add(p, v, __ATOMIC_RELAXED, __HIP_MEMORY_SCOPE_AGENT); }
; #define XB_SPIN(cond, bar) do { unsigned _sp = 0; while (cond) { __builtin_amdgcn_s_sleep(1); \
;     if ((++_sp & 255u) == 0u) { if (xb_ld(&(bar)[XB_TMO])) break; if (_sp > XB_SPIN_CAP) { atomicAdd(&(bar)[XB_TMO], 1u); break; } } } } while (0)
; __device__ __forceinline__ void xcd_barrier(const XcdBarrier& b, int wave_s) {
;     asm volatile("s_waitcnt vmcnt(0)" ::: "memory");
;     __syncthreads();
;     if (wave_s == 0 && lane_id_() == 0) {
;         unsigned* bar = b.bar;
;         __builtin_amdgcn_s_waitcnt(0);
;         unsigned nloc = b.st[0], nx = b.st[1];
;         if (nloc == 0u) { xcd_barrier_complete(bar, b.x, nloc, nx); b.st[0] = nloc; b.st[1] = nx; }
;         const unsigned old = xb_add(&bar[XB_XSUB(b.x)], 1u);
;         const unsigned gen = old / nloc;
;         if (old + 1u == (gen + 1u) * nloc) {
;             __builtin_amdgcn_fence(__ATOMIC_RELEASE, "agent");
;             asm volatile("s_waitcnt vmcnt(0)" ::: "memory");
;             const unsigned og = xb_add(&bar[XB_TOP], 1u);
;             const unsigned tg = og / nx;
;             if (og + 1u == (tg + 1u) * nx) xb_add(&bar[XB_TOPGEN], 1u);
;             else XB_SPIN(xb_ld(&bar[XB_TOPGEN]) == tg, bar);
;             __builtin_amdgcn_fence(__ATOMIC_ACQUIRE, "agent");
;             xb_add(&bar[XB_XGEN(b.x)], 1u);
;             asm volatile("s_waitcnt vmcnt(0)" ::: "memory");
;         } else {
;             XB_SPIN(xb_ld(&bar[XB_XGEN(b.x)]) == gen, bar);
;             __builtin_amdgcn_fence(__ATOMIC_ACQUIRE, "agent");
;             asm volatile("s_waitcnt vmcnt(0)" ::: "memory");
;         }
.LBB0_682:
	s_waitcnt vmcnt(0)
	s_and_b64 vcc, exec, s[2:3]
	s_waitcnt vmcnt(0)
	s_barrier
	s_cbranch_vccnz .LBB0_736
	v_mbcnt_lo_u32_b32 v0, -1, 0
	v_mbcnt_hi_u32_b32 v0, -1, v0
	s_nop 0
	v_cmp_eq_u32_e32 vcc, 0, v0
	s_and_saveexec_b64 s[6:7], vcc
	s_cbranch_execz .LBB0_735
	s_cmp_eq_u32 s101, 1
	s_cbranch_scc0 .Lglob_S4
	s_and_b32 s98, s33, 7
	s_lshl_b32 s98, s98, 8
	s_addk_i32 s98, 0x4000
	v_mov_b32_e32 v0, s98
	v_mov_b32_e32 v1, 1
	global_atomic_add v2, v0, v1, s[44:45] sc0
	s_waitcnt vmcnt(0)
	v_readfirstlane_b32 s98, v2
	s_nop 3
	s_add_u32 s99, s98, 1
	s_and_b32 s99, s99, 31
	s_lshr_b32 s98, s98, 5
	s_cmp_eq_u32 s99, 0
	s_cbranch_scc0 .Llw_S4
	global_atomic_add v0, v1, s[44:45] offset:2048
	s_branch .Lla_S4
.Llw_S4:
	s_mov_b32 s99, 0
.Lls_S4:
	global_load_dword v2, v0, s[44:45] offset:2048 sc1
	s_waitcnt vmcnt(0)
	v_readfirstlane_b32 s100, v2
	s_nop 3
	s_cmp_lg_u32 s100, s98
	s_cbranch_scc1 .Lla_S4
	s_sleep 1
	s_add_u32 s99, s99, 1
	s_cmp_lt_u32 s99, 0x4000
	s_cbranch_scc1 .Lls_S4
.Lla_S4:
	s_waitcnt vmcnt(0)
	buffer_inv sc1
	s_waitcnt vmcnt(0)
	s_branch .LBB0_735
.Lglob_S4:
	s_add_i32 s8, 0, 0x21000
	v_mov_b32_e32 v0, s8
	s_waitcnt vmcnt(0) expcnt(0) lgkmcnt(0)
	ds_read_b32 v2, v0
	s_add_i32 s8, 0, 0x21004
	v_mov_b32_e32 v0, s8
	ds_read_b32 v0, v0
	s_waitcnt lgkmcnt(1)
	v_cmp_ne_u32_e32 vcc, 0, v2
	s_cbranch_vccnz .LBB0_699
	s_load_dword s8, s[0:1], 0xf8
	s_mov_b32 s23, 1
	v_mov_b32_e32 v16, 0
	s_waitcnt lgkmcnt(0)
	s_mul_i32 s22, s47, s8
	s_add_u32 s8, s44, 0x1000
	s_addc_u32 s9, s45, 0
	s_add_u32 s10, s44, 0x1100
	s_addc_u32 s11, s45, 0
	s_add_u32 s12, s44, 0x1200
	s_addc_u32 s13, s45, 0
	s_add_u32 s14, s44, 0x1300
	s_mul_i32 s22, s22, s46
	s_addc_u32 s15, s45, 0
	s_branch .LBB0_687

; __device__ __forceinline__ int lane_id_() { int l; asm volatile("v_mbcnt_lo_u32_b32 %0, -1, 0\n\tv_mbcnt_hi_u32_b32 %0, -1, %0" : "=v"(l)); return l; }
; #define LAS __attribute__((address_space(3)))
; #define AIN(k) (kin_[launder_s_(k)])
; __device__ __forceinline__ void attn_phase2(LAS unsigned char* lds, const bf16* Q, const bf16* K, const bf16* V, bf16* O, const float* qg, const float* kg, int gw, int ngw, int wave_s) {
;     int tid_ = wave_s * 64 + lane_id_(); asm volatile("" : "+v"(tid_));
;     const int lane = tid_ & 63, w = __builtin_amdgcn_readfirstlane(tid_ >> 6), hi = lane >> 5, ql = lane & 31;
;     LAS bf16* Ks = (LAS bf16*)(lds + w * (64 * KP * 2));
;     LAS bf16* Vs = Ks + 32 * KP;
;     const int skey = lane >> 3, sch = lane & 7;
;     const LAS bf16* vtb = Vs + (4 * hi + ((lane & 15) >> 2)) * KP + 16 * ((lane >> 4) & 1) + 4 * (lane & 3);
;     for (int wu = gw; wu < BATCH * NH * 32; wu += ngw) {
;         const int pq = wu & 31, bh = wu >> 5, b = bh >> 4, h = bh & 15;
;         const int qblk0 = 2 * pq, qblk1 = 2 * pq + 1;
;         bf16x8 qfa[4], qfb[4];
;     ...
;         ATT_LOADQ(qfa, qblk0);
;         ATT_LOADQ(qfb, qblk1);
;         f32x16 oa0, oa1, ob0, ob1;
; #pragma unroll
;         for (int i = 0; i < 16; ++i) { oa0[i] = 0.f; oa1[i] = 0.f; ob0[i] = 0.f; ob1[i] = 0.f; }
;         float Ra = 0.f, Rb = 0.f;
;         bool da = false, db = false;
;         v4u kr[4], vr[4];
;         int kb = qblk1;
;         const bf16* kbase = K + (size_t)(b * SEQ + skey) * D + h * HD + 8 * sch;
;         const bf16* vbase = V + (size_t)(b * SEQ + skey) * D + h * HD + 8 * sch;
; #pragma unroll
;         for (int i = 0; i < 4; ++i) { kr[i] = *(const v4u*)(kbase + (size_t)(32 * kb + 8 * i) * D); vr[i] = *(const v4u*)(vbase + (size_t)(32 * kb + 8 * i) * D); }
; __global__ void __launch_bounds__(512, 2) fwd_megakernel(Args a) {
;     ...
;     { const int vcu = (G % 8 == 0) ? (bid % 8) * (G / 8) + bid / 8 : bid;
;       attn_phase2(lds, QB, KB, VB, QB, AIN(6), AIN(7), vcu * 8 + wave, ngw, wave); }
.LBB0_736:
	s_and_b32 s7, s46, 7
	s_cmp_eq_u32 s7, 0
	s_cselect_b64 s[8:9], -1, 0
	v_writelane_b32 v255, s8, 2
	s_mov_b32 s6, 7
	s_cmp_lg_u32 s7, 0
	v_writelane_b32 v255, s9, 3
	s_mov_b32 s63, s62
	s_waitcnt lgkmcnt(0)
	s_barrier
	s_cbranch_scc1 .LBB0_738
	s_ashr_i32 s8, s33, 31
	s_lshr_b32 s8, s8, 29
	s_add_i32 s8, s33, s8
	s_and_b32 s9, s8, 0x1ffffff8
	s_lshr_b32 s7, s46, 3
	s_lshl_b32 s7, s7, s101
	s_sub_i32 s9, s33, s9
	s_mul_i32 s7, s7, s9
	s_lshr_b32 s8, s8, 3
	s_add_i32 s7, s7, s8
	s_lshl_b32 s7, s7, 3
	v_readlane_b32 s8, v255, 0
	s_add_i32 s63, s7, s8
.LBB0_738:
	s_mul_i32 s98, s101, 3
	s_lshr_b32 s99, s54, s98
	s_lshl_b32 s100, s101, 9
	s_add_i32 s100, s100, s63
	s_cmp_eq_u32 s101, 1
	s_cselect_b32 s100, s100, 0x1000
	s_add_u32 s58, s44, 0x9400000
	s_addc_u32 s59, s45, 0
	s_add_u32 s52, s44, 0xb400000
	s_mov_b32 s8, 6
	s_addc_u32 s53, s45, 0
	v_mbcnt_lo_u32_b32 v0, -1, 0
	v_mbcnt_hi_u32_b32 v0, -1, v0
	s_cmpk_gt_i32 s63, 0xfff
	v_add_u32_e32 v1, s83, v0
	s_nop 0
	v_readfirstlane_b32 s10, v1
	s_cbranch_scc1 .LBB0_749
	s_ashr_i32 s9, s8, 31
	s_lshl_b64 s[8:9], s[8:9], 3
	s_add_u32 s8, s0, s8
	s_addc_u32 s9, s1, s9
	s_ashr_i32 s7, s6, 31
	s_lshl_b64 s[6:7], s[6:7], 3
	s_add_u32 s6, s0, s6
	s_addc_u32 s7, s1, s7
	s_load_dwordx2 s[8:9], s[8:9], 0x0
	s_nop 0
	s_load_dwordx2 s[12:13], s[6:7], 0x0
	s_lshr_b32 s6, s10, 6
	v_bfe_u32 v5, v1, 5, 1
	s_mulk_i32 s6, 0x2400
	s_add_i32 s42, s6, 0
	v_lshlrev_b32_e32 v8, 2, v5
	v_lshrrev_b32_e32 v0, 2, v1
	v_and_or_b32 v0, v0, 3, v8
	s_movk_i32 s6, 0x90
	v_mov_b32_e32 v2, s42
	v_mad_u32_u24 v0, v0, s6, v2
	v_and_b32_e32 v2, 16, v1
	v_lshlrev_b32_e32 v4, 3, v1
	v_lshlrev_b32_e32 v2, 1, v2
	v_and_b32_e32 v6, 24, v4
	v_add3_u32 v177, v0, v2, v6
	v_mbcnt_hi_u32_b32 v6, -1, v254
	v_and_b32_e32 v9, 64, v6
	v_xor_b32_e32 v7, 32, v6
	v_add_u32_e32 v9, 64, v9
	v_cmp_lt_i32_e32 vcc, v7, v9
	v_mov_b32_e32 v0, 0
	v_and_b32_e32 v175, 31, v1
	v_cndmask_b32_e32 v6, v6, v7, vcc
	v_lshlrev_b32_e32 v178, 2, v6
	v_and_b32_e32 v6, 32, v1
	v_mov_b32_e32 v7, v0
	s_waitcnt lgkmcnt(0)
	v_lshl_add_u64 v[160:161], s[8:9], 0, v[6:7]
	v_lshl_add_u64 v[162:163], s[12:13], 0, v[6:7]
	v_or_b32_e32 v7, 1, v8
	v_cmp_lt_u32_e64 s[10:11], v7, v175
	v_or_b32_e32 v7, 2, v8
	v_cmp_lt_u32_e64 s[12:13], v7, v175
	v_or_b32_e32 v7, 3, v8
	v_cmp_lt_u32_e64 s[14:15], v7, v175
	v_or_b32_e32 v7, 8, v8
	v_cmp_lt_u32_e64 s[16:17], v7, v175
	v_or_b32_e32 v7, 9, v8
	v_cmp_lt_u32_e64 s[18:19], v7, v175
	v_or_b32_e32 v7, 10, v8
	v_cmp_lt_u32_e64 s[20:21], v7, v175
	v_or_b32_e32 v7, 11, v8
	v_cmp_lt_u32_e64 s[22:23], v7, v175
	v_or_b32_e32 v7, 16, v8
	v_cmp_lt_u32_e64 s[24:25], v7, v175
	v_or_b32_e32 v7, 17, v8
	v_cmp_lt_u32_e64 s[26:27], v7, v175
	v_or_b32_e32 v7, 18, v8
	v_cmp_lt_u32_e64 s[28:29], v7, v175
	v_or_b32_e32 v7, 19, v8
	v_cmp_lt_u32_e64 s[30:31], v7, v175
	v_or_b32_e32 v7, 24, v8
	v_cmp_lt_u32_e64 s[34:35], v7, v175
	v_or_b32_e32 v7, 25, v8
	v_bfe_u32 v176, v1, 3, 3
	v_and_b32_e32 v4, 56, v4
	v_cmp_lt_u32_e64 s[36:37], v7, v175
	v_or_b32_e32 v7, 26, v8
	v_lshl_add_u32 v9, v4, 1, s42
	v_mul_u32_u24_e32 v6, 0x48, v176
	v_cmp_lt_u32_e64 s[38:39], v7, v175
	v_or_b32_e32 v7, 27, v8
	v_and_b32_e32 v3, 63, v1
	v_lshlrev_b32_e32 v2, 3, v5
	v_lshl_add_u32 v10, v5, 4, s42
	v_lshl_add_u32 v179, v6, 1, v9
	v_or_b32_e32 v6, 8, v176
	v_cmp_lt_u32_e64 s[40:41], v7, v175
	v_mul_u32_u24_e32 v5, 0x240, v5
	v_lshlrev_b32_e32 v7, 1, v175
	v_and_b32_e32 v1, 7, v1
	v_mul_u32_u24_e32 v11, 0x90, v175
	v_cmp_gt_u32_e64 s[6:7], 32, v3
	v_mul_u32_u24_e32 v3, 0x90, v176
	v_add3_u32 v180, s42, v5, v7
	v_mul_u32_u24_e32 v5, 0x90, v6
	v_lshlrev_b32_e32 v6, 4, v1
	v_mov_b32_e32 v7, v0
	v_lshlrev_b32_e32 v168, 1, v4
	s_mov_b32 s73, 0
	v_cmp_lt_u32_e64 s[8:9], v8, v175
	v_lshl_add_u64 v[164:165], s[44:45], 0, v[6:7]
	s_lshl_b32 s82, s63, 1
	s_lshl_b32 s87, s46, 4
	s_lshr_b32 s87, s87, s98
	s_lshl_b32 s88, s63, 2
	s_lshl_b32 s89, s46, 5
	s_lshr_b32 s89, s89, s98
	v_lshlrev_b32_e32 v166, 1, v2
	v_mov_b32_e32 v167, v0
	v_mov_b32_e32 v181, 0x358637bd
	s_movk_i32 s90, 0x4000
	s_mov_b32 s91, 0xc000
	s_mov_b32 s92, 0x4266d4ca
	v_add_u32_e32 v182, v9, v3
	v_add_u32_e32 v183, v9, v5
	v_mov_b32_e32 v170, v168
	v_mov_b32_e32 v171, v0
	v_add_u32_e32 v184, v10, v11
	v_mov_b32_e32 v185, 0xf149f2ca
	s_branch .LBB0_741
; __device__ __forceinline__ void attn_phase2(LAS unsigned char* lds, const bf16* Q, const bf16* K, const bf16* V, bf16* O, const float* qg, const float* kg, int gw, int ngw, int wave_s) {
;     ...
;         ATT_STORE(oa0, oa1, qblk0);
;         ATT_STORE(ob0, ob1, qblk1);
.LBB0_740:
	v_cvt_pk_bf16_f32 v1, v64, s0
	ds_write_b16 v180, v1
	v_cvt_pk_bf16_f32 v1, v48, s0
	ds_write_b16 v180, v1 offset:64
	v_cvt_pk_bf16_f32 v1, v65, s0
	ds_write_b16 v180, v1 offset:144
	v_cvt_pk_bf16_f32 v1, v49, s0
	ds_write_b16 v180, v1 offset:208
	v_cvt_pk_bf16_f32 v1, v66, s0
	ds_write_b16 v180, v1 offset:288
	v_cvt_pk_bf16_f32 v1, v50, s0
	ds_write_b16 v180, v1 offset:352
	v_cvt_pk_bf16_f32 v1, v67, s0
	ds_write_b16 v180, v1 offset:432
	v_cvt_pk_bf16_f32 v1, v51, s0
	ds_write_b16 v180, v1 offset:496
	v_cvt_pk_bf16_f32 v1, v68, s0
	ds_write_b16 v180, v1 offset:1152
	v_cvt_pk_bf16_f32 v1, v52, s0
	ds_write_b16 v180, v1 offset:1216
	v_cvt_pk_bf16_f32 v1, v69, s0
	ds_write_b16 v180, v1 offset:1296
	v_cvt_pk_bf16_f32 v1, v53, s0
	ds_write_b16 v180, v1 offset:1360
	v_cvt_pk_bf16_f32 v1, v70, s0
	ds_write_b16 v180, v1 offset:1440
	v_cvt_pk_bf16_f32 v1, v54, s0
	ds_write_b16 v180, v1 offset:1504
	v_cvt_pk_bf16_f32 v1, v71, s0
	ds_write_b16 v180, v1 offset:1584
	v_cvt_pk_bf16_f32 v1, v55, s0
	ds_write_b16 v180, v1 offset:1648
	v_cvt_pk_bf16_f32 v1, v72, s0
	ds_write_b16 v180, v1 offset:2304
	v_cvt_pk_bf16_f32 v1, v56, s0
	ds_write_b16 v180, v1 offset:2368
	v_cvt_pk_bf16_f32 v1, v73, s0
	ds_write_b16 v180, v1 offset:2448
	v_cvt_pk_bf16_f32 v1, v57, s0
	ds_write_b16 v180, v1 offset:2512
	v_cvt_pk_bf16_f32 v1, v74, s0
	ds_write_b16 v180, v1 offset:2592
	v_cvt_pk_bf16_f32 v1, v58, s0
	ds_write_b16 v180, v1 offset:2656
	v_cvt_pk_bf16_f32 v1, v75, s0
	ds_write_b16 v180, v1 offset:2736
	v_cvt_pk_bf16_f32 v1, v59, s0
	ds_write_b16 v180, v1 offset:2800
	v_cvt_pk_bf16_f32 v1, v76, s0
	ds_write_b16 v180, v1 offset:3456
	v_cvt_pk_bf16_f32 v1, v60, s0
	ds_write_b16 v180, v1 offset:3520
	v_cvt_pk_bf16_f32 v1, v77, s0
	ds_write_b16 v180, v1 offset:3600
	v_cvt_pk_bf16_f32 v1, v61, s0
	ds_write_b16 v180, v1 offset:3664
	v_cvt_pk_bf16_f32 v1, v78, s0
	ds_write_b16 v180, v1 offset:3744
	v_cvt_pk_bf16_f32 v1, v62, s0
	ds_write_b16 v180, v1 offset:3808
	v_cvt_pk_bf16_f32 v1, v79, s0
	v_or_b32_e32 v2, s95, v176
	ds_write_b16 v180, v1 offset:3888
	v_cvt_pk_bf16_f32 v1, v63, s0
	v_ashrrev_i32_e32 v3, 31, v2
	ds_write_b16 v180, v1 offset:3952
	v_lshlrev_b64 v[2:3], 11, v[2:3]
	v_lshl_add_u64 v[6:7], s[50:51], 0, v[2:3]
	s_lshl_b32 s72, s94, 1
	ds_read_b128 v[2:5], v182
	v_lshl_add_u64 v[6:7], v[6:7], 0, s[72:73]
	v_mov_b32_e32 v169, v0
	v_lshl_add_u64 v[10:11], v[6:7], 0, v[168:169]
	ds_read_b128 v[6:9], v183
	s_waitcnt lgkmcnt(1)
	global_store_dwordx4 v[10:11], v[2:5], off
	v_cvt_pk_bf16_f32 v1, v32, s0
	s_mov_b32 s42, 0x8000
	v_add_co_u32_e32 v2, vcc, s90, v10
	s_add_i32 s63, s63, s99
	s_nop 0
	v_addc_co_u32_e32 v3, vcc, 0, v11, vcc
	s_waitcnt lgkmcnt(0)
	global_store_dwordx4 v[2:3], v[6:9], off
	ds_read_b128 v[2:5], v183 offset:1152
	ds_read_b128 v[6:9], v183 offset:2304
	ds_write_b16 v180, v1
	v_cvt_pk_bf16_f32 v1, v16, s0
	ds_write_b16 v180, v1 offset:64
	v_cvt_pk_bf16_f32 v1, v33, s0
	ds_write_b16 v180, v1 offset:144
	v_cvt_pk_bf16_f32 v1, v17, s0
	ds_write_b16 v180, v1 offset:208
	v_cvt_pk_bf16_f32 v1, v34, s0
	ds_write_b16 v180, v1 offset:288
	v_cvt_pk_bf16_f32 v1, v18, s0
	ds_write_b16 v180, v1 offset:352
	v_cvt_pk_bf16_f32 v1, v35, s0
	ds_write_b16 v180, v1 offset:432
	v_cvt_pk_bf16_f32 v1, v19, s0
	ds_write_b16 v180, v1 offset:496
	v_cvt_pk_bf16_f32 v1, v36, s0
	ds_write_b16 v180, v1 offset:1152
	v_cvt_pk_bf16_f32 v1, v20, s0
	ds_write_b16 v180, v1 offset:1216
	v_cvt_pk_bf16_f32 v1, v37, s0
	ds_write_b16 v180, v1 offset:1296
	v_cvt_pk_bf16_f32 v1, v21, s0
	ds_write_b16 v180, v1 offset:1360
	v_cvt_pk_bf16_f32 v1, v38, s0
	ds_write_b16 v180, v1 offset:1440
	v_cvt_pk_bf16_f32 v1, v22, s0
	ds_write_b16 v180, v1 offset:1504
	v_cvt_pk_bf16_f32 v1, v39, s0
	ds_write_b16 v180, v1 offset:1584
	v_cvt_pk_bf16_f32 v1, v23, s0
	ds_write_b16 v180, v1 offset:1648
	v_cvt_pk_bf16_f32 v1, v40, s0
	ds_write_b16 v180, v1 offset:2304
	v_cvt_pk_bf16_f32 v1, v24, s0
	ds_write_b16 v180, v1 offset:2368
	v_cvt_pk_bf16_f32 v1, v41, s0
	ds_write_b16 v180, v1 offset:2448
	v_cvt_pk_bf16_f32 v1, v25, s0
	ds_write_b16 v180, v1 offset:2512
	v_cvt_pk_bf16_f32 v1, v42, s0
	ds_write_b16 v180, v1 offset:2592
	v_cvt_pk_bf16_f32 v1, v26, s0
	ds_write_b16 v180, v1 offset:2656
	v_cvt_pk_bf16_f32 v1, v43, s0
	ds_write_b16 v180, v1 offset:2736
	v_cvt_pk_bf16_f32 v1, v27, s0
	ds_write_b16 v180, v1 offset:2800
	v_cvt_pk_bf16_f32 v1, v44, s0
	ds_write_b16 v180, v1 offset:3456
	v_cvt_pk_bf16_f32 v1, v28, s0
	v_add_co_u32_e32 v12, vcc, s42, v10
	ds_write_b16 v180, v1 offset:3520
	v_cvt_pk_bf16_f32 v1, v45, s0
	v_addc_co_u32_e32 v13, vcc, 0, v11, vcc
	ds_write_b16 v180, v1 offset:3600
	v_cvt_pk_bf16_f32 v1, v29, s0
	s_waitcnt lgkmcnt(14)
	global_store_dwordx4 v[12:13], v[2:5], off
	ds_write_b16 v180, v1 offset:3664
	v_cvt_pk_bf16_f32 v1, v46, s0
	v_add_co_u32_e32 v2, vcc, s91, v10
	ds_write_b16 v180, v1 offset:3744
	s_nop 0
	v_addc_co_u32_e32 v3, vcc, 0, v11, vcc
	v_cvt_pk_bf16_f32 v1, v30, s0
	global_store_dwordx4 v[2:3], v[6:9], off
	ds_write_b16 v180, v1 offset:3808
	v_cvt_pk_bf16_f32 v1, v47, s0
	v_or_b32_e32 v2, s93, v176
	ds_write_b16 v180, v1 offset:3888
	v_cvt_pk_bf16_f32 v1, v31, s0
	v_ashrrev_i32_e32 v3, 31, v2
	ds_write_b16 v180, v1 offset:3952
	v_lshlrev_b64 v[6:7], 11, v[2:3]
	ds_read_b128 v[2:5], v182
	v_lshl_add_u64 v[6:7], s[50:51], 0, v[6:7]
	v_lshl_add_u64 v[6:7], v[6:7], 0, s[72:73]
	v_lshl_add_u64 v[10:11], v[6:7], 0, v[168:169]
	ds_read_b128 v[6:9], v183
	s_waitcnt lgkmcnt(1)
	global_store_dwordx4 v[10:11], v[2:5], off
	s_add_i32 s82, s82, s87
	s_add_i32 s88, s88, s89
	v_add_co_u32_e32 v2, vcc, s90, v10
	s_cmp_lt_i32 s63, s100
	s_nop 0
	v_addc_co_u32_e32 v3, vcc, 0, v11, vcc
	s_waitcnt lgkmcnt(0)
	global_store_dwordx4 v[2:3], v[6:9], off
	ds_read_b128 v[2:5], v183 offset:1152
	ds_read_b128 v[6:9], v183 offset:2304
	v_add_co_u32_e32 v12, vcc, 0x8000, v10
	s_nop 1
	v_addc_co_u32_e32 v13, vcc, 0, v11, vcc
	s_waitcnt lgkmcnt(1)
	global_store_dwordx4 v[12:13], v[2:5], off
	s_nop 1
	v_add_co_u32_e32 v2, vcc, 0xc000, v10
	s_nop 1
	v_addc_co_u32_e32 v3, vcc, 0, v11, vcc
	s_waitcnt lgkmcnt(0)
	global_store_dwordx4 v[2:3], v[6:9], off
	s_cbranch_scc0 .LBB0_749

; __device__ __forceinline__ int lane_id_() { int l; asm volatile("v_mbcnt_lo_u32_b32 %0, -1, 0\n\tv_mbcnt_hi_u32_b32 %0, -1, %0" : "=v"(l)); return l; }
; __device__ __forceinline__ unsigned xb_add(unsigned* p, unsigned v) { return __hip_atomic_fetch_add(p, v, __ATOMIC_RELAXED, __HIP_MEMORY_SCOPE_AGENT); }
; __device__ __forceinline__ void xcd_barrier(const XcdBarrier& b, int wave_s) {
;     asm volatile("s_waitcnt vmcnt(0)" ::: "memory");
;     __syncthreads();
;     if (wave_s == 0 && lane_id_() == 0) {
;         unsigned* bar = b.bar;
;         __builtin_amdgcn_s_waitcnt(0);
;         unsigned nloc = b.st[0], nx = b.st[1];
;         if (nloc == 0u) { xcd_barrier_complete(bar, b.x, nloc, nx); b.st[0] = nloc; b.st[1] = nx; }
;         const unsigned old = xb_add(&bar[XB_XSUB(b.x)], 1u);
;         const unsigned gen = old / nloc;
;         if (old + 1u == (gen + 1u) * nloc) {
.LBB0_749:
	s_waitcnt vmcnt(0)
	s_and_b64 vcc, exec, s[2:3]
	s_barrier
	s_cbranch_vccnz .LBB0_803
	v_mbcnt_lo_u32_b32 v0, -1, 0
	v_mbcnt_hi_u32_b32 v0, -1, v0
	s_nop 0
	v_cmp_eq_u32_e32 vcc, 0, v0
	s_and_saveexec_b64 s[6:7], vcc
	s_cbranch_execz .LBB0_802
	s_cmp_eq_u32 s101, 1
	s_cbranch_scc0 .Lglob_S5
	s_and_b32 s98, s33, 7
	s_lshl_b32 s98, s98, 8
	s_addk_i32 s98, 0x4000
	v_mov_b32_e32 v0, s98
	v_mov_b32_e32 v1, 1
	global_atomic_add v2, v0, v1, s[44:45] sc0
	s_waitcnt vmcnt(0)
	v_readfirstlane_b32 s98, v2
	s_nop 3
	s_add_u32 s99, s98, 1
	s_and_b32 s99, s99, 31
	s_lshr_b32 s98, s98, 5
	s_cmp_eq_u32 s99, 0
	s_cbranch_scc0 .Llw_S5
	global_atomic_add v0, v1, s[44:45] offset:2048
	s_branch .Lla_S5

; __device__ __forceinline__ int lane_id_() { int l; asm volatile("v_mbcnt_lo_u32_b32 %0, -1, 0\n\tv_mbcnt_hi_u32_b32 %0, -1, %0" : "=v"(l)); return l; }
; __device__ __forceinline__ unsigned xb_add(unsigned* p, unsigned v) { return __hip_atomic_fetch_add(p, v, __ATOMIC_RELAXED, __HIP_MEMORY_SCOPE_AGENT); }
; __device__ __forceinline__ void xcd_barrier(const XcdBarrier& b, int wave_s) {
;     asm volatile("s_waitcnt vmcnt(0)" ::: "memory");
;     __syncthreads();
;     if (wave_s == 0 && lane_id_() == 0) {
;         unsigned* bar = b.bar;
;         __builtin_amdgcn_s_waitcnt(0);
;         unsigned nloc = b.st[0], nx = b.st[1];
;         if (nloc == 0u) { xcd_barrier_complete(bar, b.x, nloc, nx); b.st[0] = nloc; b.st[1] = nx; }
;         const unsigned old = xb_add(&bar[XB_XSUB(b.x)], 1u);
;         const unsigned gen = old / nloc;
;         if (old + 1u == (gen + 1u) * nloc) {
.LBB0_1213:
	s_waitcnt vmcnt(0)
	s_and_b64 vcc, exec, s[2:3]
	s_waitcnt lgkmcnt(0)
	s_barrier
	s_cbranch_vccnz .LBB0_1267
	v_mbcnt_lo_u32_b32 v0, -1, 0
	v_mbcnt_hi_u32_b32 v0, -1, v0
	s_nop 0
	v_cmp_eq_u32_e32 vcc, 0, v0
	s_and_saveexec_b64 s[8:9], vcc
	s_cbranch_execz .LBB0_1266
	s_cmp_eq_u32 s101, 1
	s_cbranch_scc0 .Lglob_S8
	s_and_b32 s98, s33, 7
	s_lshl_b32 s98, s98, 8
	s_addk_i32 s98, 0x4000
	v_mov_b32_e32 v0, s98
	v_mov_b32_e32 v1, 1
	global_atomic_add v2, v0, v1, s[44:45] sc0
	s_waitcnt vmcnt(0)
	v_readfirstlane_b32 s98, v2
	s_nop 3
	s_add_u32 s99, s98, 1
	s_and_b32 s99, s99, 31
	s_lshr_b32 s98, s98, 5
	s_cmp_eq_u32 s99, 0
	s_cbranch_scc0 .Llw_S8
	global_atomic_add v0, v1, s[44:45] offset:2048
	s_branch .Lla_S8

; __device__ __forceinline__ int lane_id_() { int l; asm volatile("v_mbcnt_lo_u32_b32 %0, -1, 0\n\tv_mbcnt_hi_u32_b32 %0, -1, %0" : "=v"(l)); return l; }
; __device__ __forceinline__ unsigned xb_ld(unsigned* p)              { return __hip_atomic_load(p, __ATOMIC_RELAXED, __HIP_MEMORY_SCOPE_AGENT); }
; __device__ __forceinline__ void xcd_barrier_complete(unsigned* bar, unsigned x, unsigned& nloc, unsigned& nx) {
;     const unsigned G = gridDim.x * gridDim.y * gridDim.z;
;     unsigned sum, cnt, mine, sp = 0u;
;     for (;;) {
;         sum = 0u; cnt = 0u; mine = 0u;
; #pragma unroll
;         for (unsigned j = 0; j < 16; ++j) { const unsigned c = xb_ld(&bar[XB_XCNT(j)]); sum += c; cnt += (c > 0u) ? 1u : 0u; mine = (j == x) ? c : mine; }
;         if (sum == G) break;
;         __builtin_amdgcn_s_sleep(1);
;         if ((++sp & 255u) == 0u) { if (xb_ld(&bar[XB_TMO])) break; if (sp > XB_SPIN_CAP) { atomicAdd(&bar[XB_TMO], 1u); break; } }
;     }
;     nloc = mine > 0u ? mine : 1u; nx = cnt > 0u ? cnt : 1u;
; }
; __device__ __forceinline__ void xcd_barrier(const XcdBarrier& b, int wave_s) {
;     asm volatile("s_waitcnt vmcnt(0)" ::: "memory");
;     __syncthreads();
;     if (wave_s == 0 && lane_id_() == 0) {
;         unsigned* bar = b.bar;
;         __builtin_amdgcn_s_waitcnt(0);
;         unsigned nloc = b.st[0], nx = b.st[1];
;         if (nloc == 0u) { xcd_barrier_complete(bar, b.x, nloc, nx); b.st[0] = nloc; b.st[1] = nx; }
.Lglob_S8:
	s_add_i32 s6, 0, 0x21000
	v_mov_b32_e32 v0, s6
	s_waitcnt vmcnt(0) expcnt(0) lgkmcnt(0)
	ds_read_b32 v2, v0
	s_add_i32 s6, 0, 0x21004
	v_mov_b32_e32 v0, s6
	ds_read_b32 v0, v0
	s_waitcnt lgkmcnt(1)
	v_cmp_ne_u32_e32 vcc, 0, v2
	s_cbranch_vccnz .LBB0_1230
	s_add_u32 s10, s44, 0x1000
	s_load_dword s6, s[0:1], 0xf8
	s_addc_u32 s11, s45, 0
	s_add_u32 s12, s44, 0x1100
	s_addc_u32 s13, s45, 0
	s_add_u32 s20, s44, 0x1200
	s_addc_u32 s21, s45, 0
	s_waitcnt lgkmcnt(0)
	s_mul_i32 s6, s47, s6
	s_add_u32 s22, s44, 0x1300
	s_mul_i32 s6, s6, s46
	s_addc_u32 s23, s45, 0
	s_mov_b32 s7, 1
	v_mov_b32_e32 v16, 0
	s_branch .LBB0_1218

; __device__ __forceinline__ int lane_id_() { int l; asm volatile("v_mbcnt_lo_u32_b32 %0, -1, 0\n\tv_mbcnt_hi_u32_b32 %0, -1, %0" : "=v"(l)); return l; }
; __device__ __forceinline__ unsigned xb_add(unsigned* p, unsigned v) { return __hip_atomic_fetch_add(p, v, __ATOMIC_RELAXED, __HIP_MEMORY_SCOPE_AGENT); }
; __device__ __forceinline__ void xcd_barrier(const XcdBarrier& b, int wave_s) {
;     asm volatile("s_waitcnt vmcnt(0)" ::: "memory");
;     __syncthreads();
;     if (wave_s == 0 && lane_id_() == 0) {
;         unsigned* bar = b.bar;
;         __builtin_amdgcn_s_waitcnt(0);
;         unsigned nloc = b.st[0], nx = b.st[1];
;         if (nloc == 0u) { xcd_barrier_complete(bar, b.x, nloc, nx); b.st[0] = nloc; b.st[1] = nx; }
;         const unsigned old = xb_add(&bar[XB_XSUB(b.x)], 1u);
;         const unsigned gen = old / nloc;
;         if (old + 1u == (gen + 1u) * nloc) {
.LBB0_1589:
	s_waitcnt vmcnt(0)
	s_and_b64 vcc, exec, s[2:3]
	s_waitcnt vmcnt(0)
	s_barrier
	s_cbranch_vccnz .LBB0_1643
	v_mbcnt_lo_u32_b32 v0, -1, 0
	v_mbcnt_hi_u32_b32 v0, -1, v0
	s_nop 0
	v_cmp_eq_u32_e32 vcc, 0, v0
	s_and_saveexec_b64 s[8:9], vcc
	s_cbranch_execz .LBB0_1642
	s_cmp_eq_u32 s101, 1
	s_cbranch_scc0 .Lglob_S9
	s_and_b32 s98, s33, 7
	s_lshl_b32 s98, s98, 8
	s_addk_i32 s98, 0x4000
	v_mov_b32_e32 v0, s98
	v_mov_b32_e32 v1, 1
	global_atomic_add v2, v0, v1, s[44:45] sc0
	s_waitcnt vmcnt(0)
	v_readfirstlane_b32 s98, v2
	s_nop 3
	s_add_u32 s99, s98, 1
	s_and_b32 s99, s99, 31
	s_lshr_b32 s98, s98, 5
	s_cmp_eq_u32 s99, 0
	s_cbranch_scc0 .Llw_S9
	global_atomic_add v0, v1, s[44:45] offset:2048
	s_branch .Lla_S9

; __device__ __forceinline__ int lane_id_() { int l; asm volatile("v_mbcnt_lo_u32_b32 %0, -1, 0\n\tv_mbcnt_hi_u32_b32 %0, -1, %0" : "=v"(l)); return l; }
; __device__ __forceinline__ unsigned xb_ld(unsigned* p)              { return __hip_atomic_load(p, __ATOMIC_RELAXED, __HIP_MEMORY_SCOPE_AGENT); }
; __device__ __forceinline__ void xcd_barrier_complete(unsigned* bar, unsigned x, unsigned& nloc, unsigned& nx) {
;     const unsigned G = gridDim.x * gridDim.y * gridDim.z;
;     unsigned sum, cnt, mine, sp = 0u;
;     for (;;) {
;         sum = 0u; cnt = 0u; mine = 0u;
; #pragma unroll
;         for (unsigned j = 0; j < 16; ++j) { const unsigned c = xb_ld(&bar[XB_XCNT(j)]); sum += c; cnt += (c > 0u) ? 1u : 0u; mine = (j == x) ? c : mine; }
;         if (sum == G) break;
;         __builtin_amdgcn_s_sleep(1);
;         if ((++sp & 255u) == 0u) { if (xb_ld(&bar[XB_TMO])) break; if (sp > XB_SPIN_CAP) { atomicAdd(&bar[XB_TMO], 1u); break; } }
;     }
;     nloc = mine > 0u ? mine : 1u; nx = cnt > 0u ? cnt : 1u;
; }
; __device__ __forceinline__ void xcd_barrier(const XcdBarrier& b, int wave_s) {
;     asm volatile("s_waitcnt vmcnt(0)" ::: "memory");
;     __syncthreads();
;     if (wave_s == 0 && lane_id_() == 0) {
;         unsigned* bar = b.bar;
;         __builtin_amdgcn_s_waitcnt(0);
;         unsigned nloc = b.st[0], nx = b.st[1];
;         if (nloc == 0u) { xcd_barrier_complete(bar, b.x, nloc, nx); b.st[0] = nloc; b.st[1] = nx; }
.Lglob_S9:
	s_add_i32 s6, 0, 0x21000
	v_mov_b32_e32 v0, s6
	s_waitcnt vmcnt(0) expcnt(0) lgkmcnt(0)
	ds_read_b32 v2, v0
	s_add_i32 s6, 0, 0x21004
	v_mov_b32_e32 v0, s6
	ds_read_b32 v0, v0
	s_waitcnt lgkmcnt(1)
	v_cmp_ne_u32_e32 vcc, 0, v2
	s_cbranch_vccnz .LBB0_1606
	s_add_u32 s10, s44, 0x1000
	s_load_dword s6, s[0:1], 0xf8
	s_addc_u32 s11, s45, 0
	s_add_u32 s12, s44, 0x1100
	s_addc_u32 s13, s45, 0
	s_add_u32 s14, s44, 0x1200
	s_addc_u32 s15, s45, 0
	s_waitcnt lgkmcnt(0)
	s_mul_i32 s6, s47, s6
	s_add_u32 s16, s44, 0x1300
	s_mul_i32 s6, s6, s46
	s_addc_u32 s17, s45, 0
	s_mov_b32 s7, 1
	v_mov_b32_e32 v16, 0
	s_branch .LBB0_1594

; __device__ __forceinline__ int lane_id_() { int l; asm volatile("v_mbcnt_lo_u32_b32 %0, -1, 0\n\tv_mbcnt_hi_u32_b32 %0, -1, %0" : "=v"(l)); return l; }
; #define LAS __attribute__((address_space(3)))
; #define AIN(k) (kin_[launder_s_(k)])
; __device__ __forceinline__ void lru_phase(LAS unsigned char* lds, const bf16* XB, const bf16* Y, bf16* HY, const bf16* WRt, const bf16* WIt,
;         const float* convw, const float* convb, const float* br, const float* bi, const float* lam, unsigned long long* gran, int G, int bid, int wave_s) {
;     int tid = wave_s * 64 + lane_id_(); asm volatile("" : "+v"(tid));
;     const int lane = tid & 63, w = __builtin_amdgcn_readfirstlane(tid >> 6), hi = lane >> 5, ql = lane & 31;
;     LAS float* xcF = (LAS float*)lds;
;     LAS bf16* wL = (LAS bf16*)(lds + 32768);
;     LAS bf16* xcB = (LAS bf16*)(lds + 65536);
;     LAS float* segA = (LAS float*)(lds + 65536 + 128 * KP * 2);
;     LAS float* segH = segA + 512;
;     LAS float* pA = segH + 512;
;     LAS float* pH = pA + 1024;
;     LAS bf16* yL = (LAS bf16*)(lds + 65536 + 128 * KP * 2 + 16384);
;     const int st = tid >> 3, cc = 8 * (tid & 7);
;     LAS float* parL = (LAS float*)(lds + 118784);
;     int n_loaded = -1;
;     const int rb = w >> 1, cbk = w & 1, d = 32 * cbk + ql;
;     v4u xt[2][4], yv[2];
;     ...
;     if (bid < BATCH * 16 * NCH) LRU_LOAD_X(bid);
; __global__ void __launch_bounds__(512, 2) fwd_megakernel(Args a) {
;     ...
;     lru_phase(lds, QB, KB, VB, (const bf16*)(ws + W_GR), (const bf16*)(ws + W_GI), AIN(17), AIN(18), AIN(20), AIN(22), AIN(23), (unsigned long long*)(ws + WS_SUM), G, (G % 8 == 0) ? (bid % 8) * (G / 8) + bid / 8 : bid, wave);
.LBB0_2081:
	s_mov_b32 s6, 17
	s_waitcnt lgkmcnt(0)
	s_barrier
	s_ashr_i32 s7, s6, 31
	s_lshl_b64 s[6:7], s[6:7], 3
	s_add_u32 s8, s0, s6
	s_mov_b32 s6, 18
	s_addc_u32 s9, s1, s7
	s_ashr_i32 s7, s6, 31
	s_lshl_b64 s[6:7], s[6:7], 3
	s_add_u32 s10, s0, s6
	s_mov_b32 s6, 20
	s_addc_u32 s11, s1, s7
	s_ashr_i32 s7, s6, 31
	s_lshl_b64 s[6:7], s[6:7], 3
	s_add_u32 s12, s0, s6
	s_mov_b32 s6, 22
	s_addc_u32 s13, s1, s7
	s_ashr_i32 s7, s6, 31
	s_lshl_b64 s[6:7], s[6:7], 3
	s_add_u32 s14, s0, s6
	s_mov_b32 s6, 23
	s_addc_u32 s15, s1, s7
	s_ashr_i32 s7, s6, 31
	s_lshl_b64 s[6:7], s[6:7], 3
	s_add_u32 s16, s0, s6
	s_addc_u32 s17, s1, s7
	v_readlane_b32 s6, v255, 2
	v_readlane_b32 s7, v255, 3
	s_andn2_b64 vcc, exec, s[6:7]
	s_cbranch_vccnz .LBB0_2083
	s_ashr_i32 s7, s33, 31
	s_lshr_b32 s7, s7, 29
	s_add_i32 s7, s33, s7
	s_and_b32 s18, s7, -8
	s_ashr_i32 s6, s46, 3
	s_sub_i32 s18, s33, s18
	s_mul_i32 s6, s6, s18
	s_ashr_i32 s7, s7, 3
	s_add_i32 s84, s6, s7
	s_cmp_eq_u32 s101, 1
	s_cbranch_scc0 .Llru_nomap
	s_lshr_b32 s98, s33, 3
	s_and_b32 s99, s33, 7
	s_lshr_b32 s100, s98, 4
	s_lshl_b32 s100, s100, 7
	s_and_b32 s98, s98, 15
	s_add_i32 s100, s100, s98
	s_lshl_b32 s99, s99, 4
	s_add_i32 s84, s100, s99
.Llru_nomap:
.LBB0_2083:
	s_load_dwordx2 s[30:31], s[8:9], 0x0
	s_load_dwordx2 s[34:35], s[10:11], 0x0
	s_load_dwordx2 s[36:37], s[12:13], 0x0
	s_load_dwordx2 s[38:39], s[14:15], 0x0
	s_load_dwordx2 s[40:41], s[16:17], 0x0
	v_mbcnt_lo_u32_b32 v0, -1, 0
	v_mbcnt_hi_u32_b32 v0, -1, v0
	s_cmpk_lt_i32 s84, 0x800
	v_add_u32_e32 v75, s83, v0
	s_cselect_b64 s[8:9], -1, 0
	v_lshlrev_b32_e32 v0, 3, v75
	v_ashrrev_i32_e32 v10, 6, v75
	v_and_b32_e32 v11, 56, v0
	v_readfirstlane_b32 s78, v10
	v_ashrrev_i32_e32 v100, 3, v75
	s_cmpk_gt_i32 s84, 0x7ff
	v_lshlrev_b32_e32 v4, 1, v11
	s_cbranch_scc1 .LBB0_2101
	s_lshl_b32 s10, s84, 7
	s_and_b32 s6, s84, 0xffffff80
	s_and_b32 s7, s10, 0x3800
	s_add_i32 s11, s7, s6
	s_and_b32 s12, s10, 0x780
	v_add_u32_e32 v0, s11, v100
	s_add_u32 s10, s58, s12
	v_mov_b32_e32 v32, 0
	s_addc_u32 s11, s59, 0
	v_mov_b32_e32 v5, v32
	v_ashrrev_i32_e32 v1, 31, v0
	v_lshl_add_u64 v[2:3], s[10:11], 0, v[4:5]
	v_lshlrev_b64 v[6:7], 11, v[0:1]
	v_lshl_add_u64 v[6:7], v[2:3], 0, v[6:7]
	global_load_dwordx4 v[36:39], v[6:7], off
	s_add_u32 s10, s50, s12
	v_mov_b32_e32 v34, v32
	v_mov_b32_e32 v35, v32
	v_add_u32_e32 v12, s6, v100
	s_addc_u32 s11, s51, 0
	s_add_i32 s6, s7, -3
	v_mov_b32_e32 v33, v32
	v_mov_b64_e32 v[42:43], v[34:35]
	v_lshl_add_u64 v[6:7], s[10:11], 0, v[4:5]
	v_cmp_lt_i32_e32 vcc, 2, v12
	v_add_u32_e32 v8, s6, v12
	v_mov_b64_e32 v[40:41], v[32:33]
	s_and_saveexec_b64 s[10:11], vcc
	s_cbranch_execz .LBB0_2086
	v_mov_b32_e32 v9, v32
	v_lshlrev_b64 v[14:15], 11, v[8:9]
	v_lshl_add_u64 v[14:15], v[6:7], 0, v[14:15]
	global_load_dwordx4 v[40:43], v[14:15], off

; __device__ __forceinline__ int lane_id_() { int l; asm volatile("v_mbcnt_lo_u32_b32 %0, -1, 0\n\tv_mbcnt_hi_u32_b32 %0, -1, %0" : "=v"(l)); return l; }
; __device__ __forceinline__ unsigned xb_add(unsigned* p, unsigned v) { return __hip_atomic_fetch_add(p, v, __ATOMIC_RELAXED, __HIP_MEMORY_SCOPE_AGENT); }
; __device__ __forceinline__ void xcd_barrier(const XcdBarrier& b, int wave_s) {
;     asm volatile("s_waitcnt vmcnt(0)" ::: "memory");
;     __syncthreads();
;     if (wave_s == 0 && lane_id_() == 0) {
;         unsigned* bar = b.bar;
;         __builtin_amdgcn_s_waitcnt(0);
;         unsigned nloc = b.st[0], nx = b.st[1];
;         if (nloc == 0u) { xcd_barrier_complete(bar, b.x, nloc, nx); b.st[0] = nloc; b.st[1] = nx; }
;         const unsigned old = xb_add(&bar[XB_XSUB(b.x)], 1u);
;         const unsigned gen = old / nloc;
;         if (old + 1u == (gen + 1u) * nloc) {
.LBB0_2397:
	s_waitcnt vmcnt(0)
	s_and_b64 vcc, exec, s[2:3]
	s_waitcnt vmcnt(0)
	s_barrier
	s_cbranch_vccnz .LBB0_2451
	v_mbcnt_lo_u32_b32 v0, -1, 0
	v_mbcnt_hi_u32_b32 v0, -1, v0
	s_nop 0
	v_cmp_eq_u32_e32 vcc, 0, v0
	s_and_saveexec_b64 s[2:3], vcc
	s_cbranch_execz .LBB0_2450
	s_cmp_eq_u32 s101, 1
	s_cbranch_scc0 .Lglob_S14
	s_and_b32 s98, s33, 7
	s_lshl_b32 s98, s98, 8
	s_addk_i32 s98, 0x4000
	v_mov_b32_e32 v0, s98
	v_mov_b32_e32 v1, 1
	global_atomic_add v2, v0, v1, s[44:45] sc0
	s_waitcnt vmcnt(0)
	v_readfirstlane_b32 s98, v2
	s_nop 3
	s_add_u32 s99, s98, 1
	s_and_b32 s99, s99, 31
	s_lshr_b32 s98, s98, 5
	s_cmp_eq_u32 s99, 0
	s_cbranch_scc0 .Llw_S14
	global_atomic_add v0, v1, s[44:45] offset:2048
	s_branch .Lla_S14

; __device__ __forceinline__ int lane_id_() { int l; asm volatile("v_mbcnt_lo_u32_b32 %0, -1, 0\n\tv_mbcnt_hi_u32_b32 %0, -1, %0" : "=v"(l)); return l; }
; __device__ __forceinline__ unsigned xb_ld(unsigned* p)              { return __hip_atomic_load(p, __ATOMIC_RELAXED, __HIP_MEMORY_SCOPE_AGENT); }
; __device__ __forceinline__ void xcd_barrier_complete(unsigned* bar, unsigned x, unsigned& nloc, unsigned& nx) {
;     const unsigned G = gridDim.x * gridDim.y * gridDim.z;
;     unsigned sum, cnt, mine, sp = 0u;
;     for (;;) {
;         sum = 0u; cnt = 0u; mine = 0u;
; #pragma unroll
;         for (unsigned j = 0; j < 16; ++j) { const unsigned c = xb_ld(&bar[XB_XCNT(j)]); sum += c; cnt += (c > 0u) ? 1u : 0u; mine = (j == x) ? c : mine; }
;         if (sum == G) break;
;         __builtin_amdgcn_s_sleep(1);
;         if ((++sp & 255u) == 0u) { if (xb_ld(&bar[XB_TMO])) break; if (sp > XB_SPIN_CAP) { atomicAdd(&bar[XB_TMO], 1u); break; } }
;     }
;     nloc = mine > 0u ? mine : 1u; nx = cnt > 0u ? cnt : 1u;
; }
; __device__ __forceinline__ void xcd_barrier(const XcdBarrier& b, int wave_s) {
;     asm volatile("s_waitcnt vmcnt(0)" ::: "memory");
;     __syncthreads();
;     if (wave_s == 0 && lane_id_() == 0) {
;         unsigned* bar = b.bar;
;         __builtin_amdgcn_s_waitcnt(0);
;         unsigned nloc = b.st[0], nx = b.st[1];
;         if (nloc == 0u) { xcd_barrier_complete(bar, b.x, nloc, nx); b.st[0] = nloc; b.st[1] = nx; }
.Lglob_S14:
	s_add_i32 s6, 0, 0x21000
	v_mov_b32_e32 v0, s6
	s_waitcnt vmcnt(0) expcnt(0) lgkmcnt(0)
	ds_read_b32 v2, v0
	s_add_i32 s6, 0, 0x21004
	v_mov_b32_e32 v0, s6
	ds_read_b32 v0, v0
	s_waitcnt lgkmcnt(1)
	v_cmp_ne_u32_e32 vcc, 0, v2
	s_cbranch_vccnz .LBB0_2414
	s_load_dword s6, s[0:1], 0xf8
	s_mov_b32 s21, 1
	v_mov_b32_e32 v16, 0
	s_waitcnt lgkmcnt(0)
	s_mul_i32 s20, s47, s6
	s_add_u32 s6, s44, 0x1000
	s_addc_u32 s7, s45, 0
	s_add_u32 s8, s44, 0x1100
	s_addc_u32 s9, s45, 0
	s_add_u32 s10, s44, 0x1200
	s_addc_u32 s11, s45, 0
	s_add_u32 s12, s44, 0x1300
	s_mul_i32 s20, s20, s46
	s_addc_u32 s13, s45, 0
	s_branch .LBB0_2402

; __global__ void __launch_bounds__(512, 2) fwd_megakernel(Args a) {
	.amdhsa_kernel _Z14fwd_megakernel4Args
		.amdhsa_group_segment_fixed_size 0
		.amdhsa_private_segment_fixed_size 0
		.amdhsa_kernarg_size 496
		.amdhsa_user_sgpr_count 2
		.amdhsa_user_sgpr_dispatch_ptr 0
		.amdhsa_user_sgpr_queue_ptr 0
		.amdhsa_user_sgpr_kernarg_segment_ptr 1
		.amdhsa_user_sgpr_dispatch_id 0
		.amdhsa_user_sgpr_kernarg_preload_length 0
		.amdhsa_user_sgpr_kernarg_preload_offset 0
		.amdhsa_user_sgpr_private_segment_size 0
		.amdhsa_uses_dynamic_stack 0
		.amdhsa_enable_private_segment 0
		.amdhsa_system_sgpr_workgroup_id_x 1
		.amdhsa_system_sgpr_workgroup_id_y 0
		.amdhsa_system_sgpr_workgroup_id_z 0
		.amdhsa_system_sgpr_workgroup_info 0
		.amdhsa_system_vgpr_workitem_id 2
		.amdhsa_next_free_vgpr 256
		.amdhsa_next_free_sgpr 102
		.amdhsa_accum_offset 256
		.amdhsa_reserve_vcc 1
		.amdhsa_float_round_mode_32 0
		.amdhsa_float_round_mode_16_64 0
		.amdhsa_float_denorm_mode_32 3
		.amdhsa_float_denorm_mode_16_64 3
		.amdhsa_dx10_clamp 1
		.amdhsa_ieee_mode 1
		.amdhsa_fp16_overflow 0
		.amdhsa_tg_split 0
		.amdhsa_exception_fp_ieee_invalid_op 0
		.amdhsa_exception_fp_denorm_src 0
		.amdhsa_exception_fp_ieee_div_zero 0
		.amdhsa_exception_fp_ieee_overflow 0
		.amdhsa_exception_fp_ieee_underflow 0
		.amdhsa_exception_fp_ieee_inexact 0
		.amdhsa_exception_int_div_zero 0
	.end_amdhsa_kernel

; __global__ void __launch_bounds__(512, 2) fwd_megakernel(Args a) {
amdhsa.kernels:
  - .agpr_count:     0
    .args:
      - .offset:         0
        .size:           240
        .value_kind:     by_value
      - .offset:         240
        .size:           4
        .value_kind:     hidden_block_count_x
      - .offset:         244
        .size:           4
        .value_kind:     hidden_block_count_y
      - .offset:         248
        .size:           4
        .value_kind:     hidden_block_count_z
      - .offset:         252
        .size:           2
        .value_kind:     hidden_group_size_x
      - .offset:         254
        .size:           2
        .value_kind:     hidden_group_size_y
      - .offset:         256
        .size:           2
        .value_kind:     hidden_group_size_z
      - .offset:         258
        .size:           2
        .value_kind:     hidden_remainder_x
      - .offset:         260
        .size:           2
        .value_kind:     hidden_remainder_y
      - .offset:         262
        .size:           2
        .value_kind:     hidden_remainder_z
      - .offset:         280
        .size:           8
        .value_kind:     hidden_global_offset_x
      - .offset:         288
        .size:           8
        .value_kind:     hidden_global_offset_y
      - .offset:         296
        .size:           8
        .value_kind:     hidden_global_offset_z
      - .offset:         304
        .size:           2
        .value_kind:     hidden_grid_dims
      - .offset:         328
        .size:           8
        .value_kind:     hidden_multigrid_sync_arg
      - .offset:         360
        .size:           4
        .value_kind:     hidden_dynamic_lds_size
    .group_segment_fixed_size: 0
    .kernarg_segment_align: 8
    .kernarg_segment_size: 496
    .language:       OpenCL C
    .language_version:
      - 2
      - 0
    .max_flat_workgroup_size: 512
    .name:           _Z14fwd_megakernel4Args
    .private_segment_fixed_size: 0
    .sgpr_count:     108
    .sgpr_spill_count: 6
    .symbol:         _Z14fwd_megakernel4Args.kd
    .uniform_work_group_size: 1
    .uses_dynamic_stack: false
    .vgpr_count:     256
    .vgpr_spill_count: 0
    .wavefront_size: 64
